# a17 + ret_local/ret_out: per-item Q and decay-parameter loads issued at item top (before the next item's prefetch), waited right after the barrier; later vmcnt waits dropped
# speedup vs baseline: 1.0203x; 1.0069x over previous
.LBB0_748:
	s_add_i32 s22, s16, s66
	s_cmpk_gt_i32 s22, 0x3ff
	s_cselect_b32 s67, 1, 0
	s_and_b32 s68, s22, 0x60
	s_cselect_b32 s68, 0, 1
	s_cmp_eq_u32 s28, 0x100
	s_cselect_b32 s67, s68, s67
	s_cmp_lg_u32 s67, 0
	s_cselect_b64 s[18:19], -1, 0
	v_add_u32_e32 v0, v65, v75
	s_and_b64 vcc, exec, s[18:19]
	s_lshr_b32 s0, s16, 4
	s_and_b32 s0, s0, 28
	v_mov_b32_e32 v57, s0
	global_load_dword v31, v57, s[50:51]
	global_load_dword v56, v57, s[52:53]
	s_waitcnt vmcnt(7)
	ds_write_b128 v79, v[32:35]
	s_waitcnt vmcnt(6)
	ds_write_b128 v79, v[36:39] offset:9216
	s_waitcnt vmcnt(5)
	ds_write_b16 v0, v40 offset:18432
	ds_write_b16_d16_hi v0, v40 offset:18704
	ds_write_b16 v0, v41 offset:18976
	ds_write_b16_d16_hi v0, v41 offset:19248
	ds_write_b16 v0, v42 offset:19520
	ds_write_b16_d16_hi v0, v42 offset:19792
	ds_write_b16 v0, v43 offset:20064
	ds_write_b16_d16_hi v0, v43 offset:20336
	s_waitcnt vmcnt(4)
	ds_write_b16 v80, v44 offset:18432
	ds_write_b16_d16_hi v80, v44 offset:18704
	ds_write_b16 v80, v45 offset:18976
	ds_write_b16_d16_hi v80, v45 offset:19248
	ds_write_b16 v80, v46 offset:19520
	ds_write_b16_d16_hi v80, v46 offset:19792
	ds_write_b16 v80, v47 offset:20064
	ds_write_b16_d16_hi v80, v47 offset:20336
	s_waitcnt vmcnt(3)
	ds_write_b16 v80, v48 offset:27136
	ds_write_b16_d16_hi v80, v48 offset:27408
	ds_write_b16 v80, v49 offset:27680
	ds_write_b16_d16_hi v80, v49 offset:27952
	ds_write_b16 v80, v50 offset:28224
	ds_write_b16_d16_hi v80, v50 offset:28496
	ds_write_b16 v80, v51 offset:28768
	ds_write_b16_d16_hi v80, v51 offset:29040
	s_waitcnt vmcnt(2)
	ds_write_b16 v80, v52 offset:35840
	ds_write_b16_d16_hi v80, v52 offset:36112
	ds_write_b16 v80, v53 offset:36384
	ds_write_b16_d16_hi v80, v53 offset:36656
	ds_write_b16 v80, v54 offset:36928
	ds_write_b16_d16_hi v80, v54 offset:37200
	ds_write_b16 v80, v55 offset:37472
	ds_write_b16_d16_hi v80, v55 offset:37744
	s_waitcnt lgkmcnt(0)
	s_barrier
	s_waitcnt vmcnt(0)
	s_cbranch_vccnz .LBB0_750
	s_ashr_i32 s38, s22, 9
	s_ashr_i32 s39, s38, 31
	s_lshl_b32 s0, s22, 7
	s_lshl_b64 s[38:39], s[38:39], 13
	s_and_b32 s0, s0, 0x1f80
	s_bfe_u32 s17, s22, 0x30006
	s_or_b32 s38, s38, s0
	v_lshl_add_u64 v[0:1], s[38:39], 0, v[66:67]
	s_lshl_b32 s0, s17, 7
	v_lshl_add_u64 v[2:3], v[70:71], 0, s[0:1]
	v_lshlrev_b64 v[0:1], 10, v[0:1]
	v_lshl_add_u64 v[0:1], v[2:3], 0, v[0:1]
	v_add_co_u32_e32 v2, vcc, s8, v0
	s_lshl_b32 s0, s17, 8
	s_nop 0
	v_addc_co_u32_e32 v3, vcc, 0, v1, vcc
	global_load_dwordx4 v[32:35], v[0:1], off
	global_load_dwordx4 v[36:39], v[2:3], off
	v_mov_b32_e32 v1, s39
	v_or_b32_e32 v0, s38, v64
	v_lshlrev_b64 v[0:1], 11, v[0:1]
	v_lshl_add_u64 v[0:1], s[12:13], 0, v[0:1]
	v_lshl_add_u64 v[0:1], v[0:1], 0, s[0:1]
	v_lshl_add_u64 v[0:1], v[68:69], 1, v[0:1]
	global_load_dwordx4 v[40:43], v[0:1], off
	global_load_dwordx4 v[44:47], v[0:1], off offset:64
	global_load_dwordx4 v[48:51], v[0:1], off offset:128
	global_load_dwordx4 v[52:55], v[0:1], off offset:192
.LBB0_750:
	v_mov_b32_e32 v0, 0
	s_mov_b32 s0, 0
	v_mov_b32_e32 v82, v78
	v_mov_b32_e32 v83, v77
	v_mov_b32_e32 v84, v76
	v_mov_b32_e32 v1, v0
	v_mov_b32_e32 v2, v0
	v_mov_b32_e32 v3, v0
	v_mov_b32_e32 v4, v0
	v_mov_b32_e32 v5, v0
	v_mov_b32_e32 v6, v0
	v_mov_b32_e32 v7, v0
	v_mov_b32_e32 v8, v0
	v_mov_b32_e32 v9, v0
	v_mov_b32_e32 v10, v0
	v_mov_b32_e32 v11, v0
	v_mov_b32_e32 v12, v0
	v_mov_b32_e32 v13, v0
	v_mov_b32_e32 v14, v0
	v_mov_b32_e32 v15, v0
	v_mov_b32_e32 v16, v0
	v_mov_b32_e32 v17, v0
	v_mov_b32_e32 v18, v0
	v_mov_b32_e32 v19, v0
	v_mov_b32_e32 v20, v0
	v_mov_b32_e32 v21, v0
	v_mov_b32_e32 v22, v0
	v_mov_b32_e32 v23, v0
	v_mov_b32_e32 v24, v0
	v_mov_b32_e32 v25, v0
	v_mov_b32_e32 v26, v0
	v_mov_b32_e32 v27, v0
	v_mov_b32_e32 v28, v0
	v_mul_f32_e32 v29, 0x3fb8aa3b, v31
	v_mul_f32_e32 v30, 0x3fb8aa3b, v56
	v_fma_f32 v57, v31, s9, -v29
	v_rndne_f32_e32 v58, v29
	v_fma_f32 v59, v56, s9, -v30
	v_rndne_f32_e32 v60, v30
	v_fmac_f32_e32 v57, 0x32a5705f, v31
	v_sub_f32_e32 v29, v29, v58
	v_fmac_f32_e32 v59, 0x32a5705f, v56
	v_sub_f32_e32 v30, v30, v60
	v_add_f32_e32 v29, v29, v57
	v_cvt_i32_f32_e32 v58, v58
	v_add_f32_e32 v30, v30, v59
	v_exp_f32_e32 v57, v29
	v_cvt_i32_f32_e32 v60, v60
	v_exp_f32_e32 v59, v30
	v_cmp_ngt_f32_e32 vcc, s20, v31
	v_ldexp_f32 v57, v57, v58
	v_mov_b32_e32 v29, v0
	v_ldexp_f32 v58, v59, v60
	v_cndmask_b32_e32 v57, 0, v57, vcc
	v_cmp_ngt_f32_e32 vcc, s20, v56
	v_mov_b32_e32 v30, v0
	s_nop 0
	v_cndmask_b32_e32 v58, 0, v58, vcc
	v_cmp_nlt_f32_e32 vcc, s21, v31
	s_nop 1
	v_cndmask_b32_e32 v31, v81, v57, vcc
	v_cmp_nlt_f32_e32 vcc, s21, v56
	v_mul_f32_e32 v85, 0xbfb8aa3b, v31
	v_mov_b32_e32 v31, v0
	v_cndmask_b32_e32 v56, v81, v58, vcc
	v_mul_f32_e32 v86, 0xbfb8aa3b, v56
	s_lshl_b32 s56, s33, 4
	s_add_i32 s56, s56, 0x18000
	v_and_b32_e32 v150, 63, v64
	v_sub_u32_e32 v151, 0x7f, v150
	v_sub_u32_e32 v152, 63, v150
	v_add_u32_e32 v153, 64, v150
	v_cvt_f32_u32_e32 v151, v151
	v_cvt_f32_u32_e32 v152, v152
	v_cvt_f32_u32_e32 v154, v150
	v_cvt_f32_u32_e32 v153, v153
	v_mul_f32_e32 v151, v85, v151
	v_mul_f32_e32 v152, v85, v152
	v_mul_f32_e32 v154, v86, v154
	v_mul_f32_e32 v153, v86, v153
	v_exp_f32_e32 v151, v151
	v_exp_f32_e32 v152, v152
	v_exp_f32_e32 v154, v154
	v_exp_f32_e32 v153, v153
	v_lshl_add_u32 v155, v150, 2, s56
	v_lshl_add_u32 v156, v74, 2, s56
	ds_write_b32 v155, v151
	ds_write_b32 v155, v152 offset:256
	ds_write_b32 v155, v154 offset:512
	ds_write_b32 v155, v153 offset:768
	ds_read_b128 v[60:63], v84
	ds_read_b128 v[56:59], v84 offset:32
	ds_read_u16 v96, v82
	ds_read_u16 v97, v82 offset:144
	ds_read_u16 v98, v82 offset:288
	ds_read_u16 v99, v82 offset:432
	ds_read_u16 v100, v82 offset:1152
	ds_read_u16 v101, v82 offset:1296
	ds_read_u16 v102, v82 offset:1440
	ds_read_u16 v103, v82 offset:1584
	ds_read_u16 v112, v82 offset:2304
	ds_read_u16 v113, v82 offset:2448
	ds_read_u16 v114, v82 offset:2592
	ds_read_u16 v115, v82 offset:2736
	ds_read_u16 v116, v82 offset:3456
	ds_read_u16 v117, v82 offset:3600
	ds_read_u16 v118, v82 offset:3744
	ds_read_u16 v119, v82 offset:3888
	ds_read_b128 v[160:163], v156
	ds_read_b128 v[164:167], v156 offset:32
	ds_read_b128 v[168:171], v156 offset:512
	ds_read_b128 v[172:175], v156 offset:544
	ds_read_b128 v[176:179], v156 offset:64
	ds_read_b128 v[180:183], v156 offset:96
	ds_read_b128 v[184:187], v156 offset:576
	ds_read_b128 v[188:191], v156 offset:608
	s_waitcnt lgkmcnt(4)
	v_lshlrev_b32_e32 v88, 16, v96
	v_lshlrev_b32_e32 v89, 16, v97
	v_lshlrev_b32_e32 v90, 16, v98
	v_lshlrev_b32_e32 v91, 16, v99
	v_lshlrev_b32_e32 v92, 16, v100
	v_lshlrev_b32_e32 v93, 16, v101
	v_lshlrev_b32_e32 v94, 16, v102
	v_lshlrev_b32_e32 v95, 16, v103
	v_pk_mul_f32 v[160:161], v[160:161], v[88:89]
	v_pk_mul_f32 v[162:163], v[162:163], v[90:91]
	v_pk_mul_f32 v[164:165], v[164:165], v[92:93]
	v_pk_mul_f32 v[166:167], v[166:167], v[94:95]
	v_pk_mul_f32 v[168:169], v[168:169], v[88:89]
	v_pk_mul_f32 v[170:171], v[170:171], v[90:91]
	v_pk_mul_f32 v[172:173], v[172:173], v[92:93]
	v_pk_mul_f32 v[174:175], v[174:175], v[94:95]
	v_cvt_pk_bf16_f32 v104, v160, v161
	v_cvt_pk_bf16_f32 v105, v162, v163
	v_cvt_pk_bf16_f32 v106, v164, v165
	v_cvt_pk_bf16_f32 v107, v166, v167
	v_cvt_pk_bf16_f32 v108, v168, v169
	v_cvt_pk_bf16_f32 v109, v170, v171
	v_cvt_pk_bf16_f32 v110, v172, v173
	v_cvt_pk_bf16_f32 v111, v174, v175
	s_nop 1
	v_mfma_f32_32x32x16_bf16 v[16:31], v[60:63], v[104:107], v[16:31]
	v_mfma_f32_32x32x16_bf16 v[0:15], v[60:63], v[108:111], v[0:15]
	s_waitcnt lgkmcnt(0)
	v_lshlrev_b32_e32 v88, 16, v112
	v_lshlrev_b32_e32 v89, 16, v113
	v_lshlrev_b32_e32 v90, 16, v114
	v_lshlrev_b32_e32 v91, 16, v115
	v_lshlrev_b32_e32 v92, 16, v116
	v_lshlrev_b32_e32 v93, 16, v117
	v_lshlrev_b32_e32 v94, 16, v118
	v_lshlrev_b32_e32 v95, 16, v119
	v_pk_mul_f32 v[176:177], v[176:177], v[88:89]
	v_pk_mul_f32 v[178:179], v[178:179], v[90:91]
	v_pk_mul_f32 v[180:181], v[180:181], v[92:93]
	v_pk_mul_f32 v[182:183], v[182:183], v[94:95]
	v_pk_mul_f32 v[184:185], v[184:185], v[88:89]
	v_pk_mul_f32 v[186:187], v[186:187], v[90:91]
	v_pk_mul_f32 v[188:189], v[188:189], v[92:93]
	v_pk_mul_f32 v[190:191], v[190:191], v[94:95]
	v_cvt_pk_bf16_f32 v120, v176, v177
	v_cvt_pk_bf16_f32 v121, v178, v179
	v_cvt_pk_bf16_f32 v122, v180, v181
	v_cvt_pk_bf16_f32 v123, v182, v183
	v_cvt_pk_bf16_f32 v124, v184, v185
	v_cvt_pk_bf16_f32 v125, v186, v187
	v_cvt_pk_bf16_f32 v126, v188, v189
	v_cvt_pk_bf16_f32 v127, v190, v191
	s_nop 1
	v_mfma_f32_32x32x16_bf16 v[16:31], v[56:59], v[120:123], v[16:31]
	v_mfma_f32_32x32x16_bf16 v[0:15], v[56:59], v[124:127], v[0:15]
	ds_read_b128 v[60:63], v84 offset:64
	ds_read_b128 v[56:59], v84 offset:96
	ds_read_u16 v96, v82 offset:4608
	ds_read_u16 v97, v82 offset:4752
	ds_read_u16 v98, v82 offset:4896
	ds_read_u16 v99, v82 offset:5040
	ds_read_u16 v100, v82 offset:5760
	ds_read_u16 v101, v82 offset:5904
	ds_read_u16 v102, v82 offset:6048
	ds_read_u16 v103, v82 offset:6192
	ds_read_u16 v112, v82 offset:6912
	ds_read_u16 v113, v82 offset:7056
	ds_read_u16 v114, v82 offset:7200
	ds_read_u16 v115, v82 offset:7344
	ds_read_u16 v116, v82 offset:8064
	ds_read_u16 v117, v82 offset:8208
	ds_read_u16 v118, v82 offset:8352
	ds_read_u16 v119, v82 offset:8496
	ds_read_b128 v[160:163], v156 offset:128
	ds_read_b128 v[164:167], v156 offset:160
	ds_read_b128 v[168:171], v156 offset:640
	ds_read_b128 v[172:175], v156 offset:672
	ds_read_b128 v[176:179], v156 offset:192
	ds_read_b128 v[180:183], v156 offset:224
	ds_read_b128 v[184:187], v156 offset:704
	ds_read_b128 v[188:191], v156 offset:736
	s_waitcnt lgkmcnt(4)
	v_lshlrev_b32_e32 v88, 16, v96
	v_lshlrev_b32_e32 v89, 16, v97
	v_lshlrev_b32_e32 v90, 16, v98
	v_lshlrev_b32_e32 v91, 16, v99
	v_lshlrev_b32_e32 v92, 16, v100
	v_lshlrev_b32_e32 v93, 16, v101
	v_lshlrev_b32_e32 v94, 16, v102
	v_lshlrev_b32_e32 v95, 16, v103
	v_pk_mul_f32 v[160:161], v[160:161], v[88:89]
	v_pk_mul_f32 v[162:163], v[162:163], v[90:91]
	v_pk_mul_f32 v[164:165], v[164:165], v[92:93]
	v_pk_mul_f32 v[166:167], v[166:167], v[94:95]
	v_pk_mul_f32 v[168:169], v[168:169], v[88:89]
	v_pk_mul_f32 v[170:171], v[170:171], v[90:91]
	v_pk_mul_f32 v[172:173], v[172:173], v[92:93]
	v_pk_mul_f32 v[174:175], v[174:175], v[94:95]
	v_cvt_pk_bf16_f32 v104, v160, v161
	v_cvt_pk_bf16_f32 v105, v162, v163
	v_cvt_pk_bf16_f32 v106, v164, v165
	v_cvt_pk_bf16_f32 v107, v166, v167
	v_cvt_pk_bf16_f32 v108, v168, v169
	v_cvt_pk_bf16_f32 v109, v170, v171
	v_cvt_pk_bf16_f32 v110, v172, v173
	v_cvt_pk_bf16_f32 v111, v174, v175
	s_nop 1
	v_mfma_f32_32x32x16_bf16 v[16:31], v[60:63], v[104:107], v[16:31]
	v_mfma_f32_32x32x16_bf16 v[0:15], v[60:63], v[108:111], v[0:15]
	s_waitcnt lgkmcnt(0)
	v_lshlrev_b32_e32 v88, 16, v112
	v_lshlrev_b32_e32 v89, 16, v113
	v_lshlrev_b32_e32 v90, 16, v114
	v_lshlrev_b32_e32 v91, 16, v115
	v_lshlrev_b32_e32 v92, 16, v116
	v_lshlrev_b32_e32 v93, 16, v117
	v_lshlrev_b32_e32 v94, 16, v118
	v_lshlrev_b32_e32 v95, 16, v119
	v_pk_mul_f32 v[176:177], v[176:177], v[88:89]
	v_pk_mul_f32 v[178:179], v[178:179], v[90:91]
	v_pk_mul_f32 v[180:181], v[180:181], v[92:93]
	v_pk_mul_f32 v[182:183], v[182:183], v[94:95]
	v_pk_mul_f32 v[184:185], v[184:185], v[88:89]
	v_pk_mul_f32 v[186:187], v[186:187], v[90:91]
	v_pk_mul_f32 v[188:189], v[188:189], v[92:93]
	v_pk_mul_f32 v[190:191], v[190:191], v[94:95]
	v_cvt_pk_bf16_f32 v120, v176, v177
	v_cvt_pk_bf16_f32 v121, v178, v179
	v_cvt_pk_bf16_f32 v122, v180, v181
	v_cvt_pk_bf16_f32 v123, v182, v183
	v_cvt_pk_bf16_f32 v124, v184, v185
	v_cvt_pk_bf16_f32 v125, v186, v187
	v_cvt_pk_bf16_f32 v126, v188, v189
	v_cvt_pk_bf16_f32 v127, v190, v191
	s_nop 1
	v_mfma_f32_32x32x16_bf16 v[16:31], v[56:59], v[120:123], v[16:31]
	v_mfma_f32_32x32x16_bf16 v[0:15], v[56:59], v[124:127], v[0:15]
	ds_read_b128 v[60:63], v84 offset:128
	ds_read_b128 v[56:59], v84 offset:160
	ds_read_u16 v96, v82 offset:9216
	ds_read_u16 v97, v82 offset:9360
	ds_read_u16 v98, v82 offset:9504
	ds_read_u16 v99, v82 offset:9648
	ds_read_u16 v100, v82 offset:10368
	ds_read_u16 v101, v82 offset:10512
	ds_read_u16 v102, v82 offset:10656
	ds_read_u16 v103, v82 offset:10800
	ds_read_u16 v112, v82 offset:11520
	ds_read_u16 v113, v82 offset:11664
	ds_read_u16 v114, v82 offset:11808
	ds_read_u16 v115, v82 offset:11952
	ds_read_u16 v116, v82 offset:12672
	ds_read_u16 v117, v82 offset:12816
	ds_read_u16 v118, v82 offset:12960
	ds_read_u16 v119, v82 offset:13104
	ds_read_b128 v[160:163], v156 offset:256
	ds_read_b128 v[164:167], v156 offset:288
	ds_read_b128 v[168:171], v156 offset:768
	ds_read_b128 v[172:175], v156 offset:800
	ds_read_b128 v[176:179], v156 offset:320
	ds_read_b128 v[180:183], v156 offset:352
	ds_read_b128 v[184:187], v156 offset:832
	ds_read_b128 v[188:191], v156 offset:864
	s_waitcnt lgkmcnt(4)
	v_lshlrev_b32_e32 v88, 16, v96
	v_lshlrev_b32_e32 v89, 16, v97
	v_lshlrev_b32_e32 v90, 16, v98
	v_lshlrev_b32_e32 v91, 16, v99
	v_lshlrev_b32_e32 v92, 16, v100
	v_lshlrev_b32_e32 v93, 16, v101
	v_lshlrev_b32_e32 v94, 16, v102
	v_lshlrev_b32_e32 v95, 16, v103
	v_pk_mul_f32 v[160:161], v[160:161], v[88:89]
	v_pk_mul_f32 v[162:163], v[162:163], v[90:91]
	v_pk_mul_f32 v[164:165], v[164:165], v[92:93]
	v_pk_mul_f32 v[166:167], v[166:167], v[94:95]
	v_pk_mul_f32 v[168:169], v[168:169], v[88:89]
	v_pk_mul_f32 v[170:171], v[170:171], v[90:91]
	v_pk_mul_f32 v[172:173], v[172:173], v[92:93]
	v_pk_mul_f32 v[174:175], v[174:175], v[94:95]
	v_cvt_pk_bf16_f32 v104, v160, v161
	v_cvt_pk_bf16_f32 v105, v162, v163
	v_cvt_pk_bf16_f32 v106, v164, v165
	v_cvt_pk_bf16_f32 v107, v166, v167
	v_cvt_pk_bf16_f32 v108, v168, v169
	v_cvt_pk_bf16_f32 v109, v170, v171
	v_cvt_pk_bf16_f32 v110, v172, v173
	v_cvt_pk_bf16_f32 v111, v174, v175
	s_nop 1
	v_mfma_f32_32x32x16_bf16 v[16:31], v[60:63], v[104:107], v[16:31]
	v_mfma_f32_32x32x16_bf16 v[0:15], v[60:63], v[108:111], v[0:15]
	s_waitcnt lgkmcnt(0)
	v_lshlrev_b32_e32 v88, 16, v112
	v_lshlrev_b32_e32 v89, 16, v113
	v_lshlrev_b32_e32 v90, 16, v114
	v_lshlrev_b32_e32 v91, 16, v115
	v_lshlrev_b32_e32 v92, 16, v116
	v_lshlrev_b32_e32 v93, 16, v117
	v_lshlrev_b32_e32 v94, 16, v118
	v_lshlrev_b32_e32 v95, 16, v119
	v_pk_mul_f32 v[176:177], v[176:177], v[88:89]
	v_pk_mul_f32 v[178:179], v[178:179], v[90:91]
	v_pk_mul_f32 v[180:181], v[180:181], v[92:93]
	v_pk_mul_f32 v[182:183], v[182:183], v[94:95]
	v_pk_mul_f32 v[184:185], v[184:185], v[88:89]
	v_pk_mul_f32 v[186:187], v[186:187], v[90:91]
	v_pk_mul_f32 v[188:189], v[188:189], v[92:93]
	v_pk_mul_f32 v[190:191], v[190:191], v[94:95]
	v_cvt_pk_bf16_f32 v120, v176, v177
	v_cvt_pk_bf16_f32 v121, v178, v179
	v_cvt_pk_bf16_f32 v122, v180, v181
	v_cvt_pk_bf16_f32 v123, v182, v183
	v_cvt_pk_bf16_f32 v124, v184, v185
	v_cvt_pk_bf16_f32 v125, v186, v187
	v_cvt_pk_bf16_f32 v126, v188, v189
	v_cvt_pk_bf16_f32 v127, v190, v191
	s_nop 1
	v_mfma_f32_32x32x16_bf16 v[16:31], v[56:59], v[120:123], v[16:31]
	v_mfma_f32_32x32x16_bf16 v[0:15], v[56:59], v[124:127], v[0:15]
	ds_read_b128 v[60:63], v84 offset:192
	ds_read_b128 v[56:59], v84 offset:224
	ds_read_u16 v96, v82 offset:13824
	ds_read_u16 v97, v82 offset:13968
	ds_read_u16 v98, v82 offset:14112
	ds_read_u16 v99, v82 offset:14256
	ds_read_u16 v100, v82 offset:14976
	ds_read_u16 v101, v82 offset:15120
	ds_read_u16 v102, v82 offset:15264
	ds_read_u16 v103, v82 offset:15408
	ds_read_u16 v112, v82 offset:16128
	ds_read_u16 v113, v82 offset:16272
	ds_read_u16 v114, v82 offset:16416
	ds_read_u16 v115, v82 offset:16560
	ds_read_u16 v116, v82 offset:17280
	ds_read_u16 v117, v82 offset:17424
	ds_read_u16 v118, v82 offset:17568
	ds_read_u16 v119, v82 offset:17712
	ds_read_b128 v[160:163], v156 offset:384
	ds_read_b128 v[164:167], v156 offset:416
	ds_read_b128 v[168:171], v156 offset:896
	ds_read_b128 v[172:175], v156 offset:928
	ds_read_b128 v[176:179], v156 offset:448
	ds_read_b128 v[180:183], v156 offset:480
	ds_read_b128 v[184:187], v156 offset:960
	ds_read_b128 v[188:191], v156 offset:992
	s_waitcnt lgkmcnt(4)
	v_lshlrev_b32_e32 v88, 16, v96
	v_lshlrev_b32_e32 v89, 16, v97
	v_lshlrev_b32_e32 v90, 16, v98
	v_lshlrev_b32_e32 v91, 16, v99
	v_lshlrev_b32_e32 v92, 16, v100
	v_lshlrev_b32_e32 v93, 16, v101
	v_lshlrev_b32_e32 v94, 16, v102
	v_lshlrev_b32_e32 v95, 16, v103
	v_pk_mul_f32 v[160:161], v[160:161], v[88:89]
	v_pk_mul_f32 v[162:163], v[162:163], v[90:91]
	v_pk_mul_f32 v[164:165], v[164:165], v[92:93]
	v_pk_mul_f32 v[166:167], v[166:167], v[94:95]
	v_pk_mul_f32 v[168:169], v[168:169], v[88:89]
	v_pk_mul_f32 v[170:171], v[170:171], v[90:91]
	v_pk_mul_f32 v[172:173], v[172:173], v[92:93]
	v_pk_mul_f32 v[174:175], v[174:175], v[94:95]
	v_cvt_pk_bf16_f32 v104, v160, v161
	v_cvt_pk_bf16_f32 v105, v162, v163
	v_cvt_pk_bf16_f32 v106, v164, v165
	v_cvt_pk_bf16_f32 v107, v166, v167
	v_cvt_pk_bf16_f32 v108, v168, v169
	v_cvt_pk_bf16_f32 v109, v170, v171
	v_cvt_pk_bf16_f32 v110, v172, v173
	v_cvt_pk_bf16_f32 v111, v174, v175
	s_nop 1
	v_mfma_f32_32x32x16_bf16 v[16:31], v[60:63], v[104:107], v[16:31]
	v_mfma_f32_32x32x16_bf16 v[0:15], v[60:63], v[108:111], v[0:15]
	s_waitcnt lgkmcnt(0)
	v_lshlrev_b32_e32 v88, 16, v112
	v_lshlrev_b32_e32 v89, 16, v113
	v_lshlrev_b32_e32 v90, 16, v114
	v_lshlrev_b32_e32 v91, 16, v115
	v_lshlrev_b32_e32 v92, 16, v116
	v_lshlrev_b32_e32 v93, 16, v117
	v_lshlrev_b32_e32 v94, 16, v118
	v_lshlrev_b32_e32 v95, 16, v119
	v_pk_mul_f32 v[176:177], v[176:177], v[88:89]
	v_pk_mul_f32 v[178:179], v[178:179], v[90:91]
	v_pk_mul_f32 v[180:181], v[180:181], v[92:93]
	v_pk_mul_f32 v[182:183], v[182:183], v[94:95]
	v_pk_mul_f32 v[184:185], v[184:185], v[88:89]
	v_pk_mul_f32 v[186:187], v[186:187], v[90:91]
	v_pk_mul_f32 v[188:189], v[188:189], v[92:93]
	v_pk_mul_f32 v[190:191], v[190:191], v[94:95]
	v_cvt_pk_bf16_f32 v120, v176, v177
	v_cvt_pk_bf16_f32 v121, v178, v179
	v_cvt_pk_bf16_f32 v122, v180, v181
	v_cvt_pk_bf16_f32 v123, v182, v183
	v_cvt_pk_bf16_f32 v124, v184, v185
	v_cvt_pk_bf16_f32 v125, v186, v187
	v_cvt_pk_bf16_f32 v126, v188, v189
	v_cvt_pk_bf16_f32 v127, v190, v191
	s_nop 1
	v_mfma_f32_32x32x16_bf16 v[16:31], v[56:59], v[120:123], v[16:31]
	v_mfma_f32_32x32x16_bf16 v[0:15], v[56:59], v[124:127], v[0:15]
	s_ashr_i32 s17, s16, 31
	s_lshl_b64 s[38:39], s[16:17], 14
	s_addk_i32 s16, 0x400
	s_ashr_i32 s17, s16, 31
	s_lshl_b64 s[16:17], s[16:17], 14
	v_cvt_pk_bf16_f32 v16, v16, s0
	v_lshl_add_u64 v[56:57], v[72:73], 0, s[38:39]
	s_nop 0
	v_cvt_pk_bf16_f32 v0, v0, s0
	v_lshl_add_u64 v[58:59], v[72:73], 0, s[16:17]
	global_store_short v[56:57], v16, off
	global_store_short v[58:59], v0, off
	v_cvt_pk_bf16_f32 v0, v17, s0
	global_store_short v[56:57], v0, off offset:128
	v_cvt_pk_bf16_f32 v0, v1, s0
	global_store_short v[58:59], v0, off offset:128
	v_cvt_pk_bf16_f32 v0, v18, s0
	global_store_short v[56:57], v0, off offset:256
	v_cvt_pk_bf16_f32 v0, v2, s0
	global_store_short v[58:59], v0, off offset:256
	v_cvt_pk_bf16_f32 v0, v19, s0
	global_store_short v[56:57], v0, off offset:384
	v_cvt_pk_bf16_f32 v0, v3, s0
	global_store_short v[58:59], v0, off offset:384
	v_cvt_pk_bf16_f32 v0, v20, s0
	global_store_short v[56:57], v0, off offset:1024
	v_cvt_pk_bf16_f32 v0, v4, s0
	global_store_short v[58:59], v0, off offset:1024
	v_cvt_pk_bf16_f32 v0, v21, s0
	global_store_short v[56:57], v0, off offset:1152
	v_cvt_pk_bf16_f32 v0, v5, s0
	global_store_short v[58:59], v0, off offset:1152
	v_cvt_pk_bf16_f32 v0, v22, s0
	global_store_short v[56:57], v0, off offset:1280
	v_cvt_pk_bf16_f32 v0, v6, s0
	global_store_short v[58:59], v0, off offset:1280
	v_cvt_pk_bf16_f32 v0, v23, s0
	global_store_short v[56:57], v0, off offset:1408
	v_cvt_pk_bf16_f32 v0, v7, s0
	global_store_short v[58:59], v0, off offset:1408
	v_cvt_pk_bf16_f32 v0, v24, s0
	global_store_short v[56:57], v0, off offset:2048
	v_cvt_pk_bf16_f32 v0, v8, s0
	global_store_short v[58:59], v0, off offset:2048
	v_cvt_pk_bf16_f32 v0, v25, s0
	global_store_short v[56:57], v0, off offset:2176
	v_cvt_pk_bf16_f32 v0, v9, s0
	global_store_short v[58:59], v0, off offset:2176
	v_cvt_pk_bf16_f32 v0, v26, s0
	global_store_short v[56:57], v0, off offset:2304
	v_cvt_pk_bf16_f32 v0, v10, s0
	global_store_short v[58:59], v0, off offset:2304
	v_cvt_pk_bf16_f32 v0, v27, s0
	global_store_short v[56:57], v0, off offset:2432
	v_cvt_pk_bf16_f32 v0, v11, s0
	global_store_short v[58:59], v0, off offset:2432
	v_cvt_pk_bf16_f32 v0, v28, s0
	global_store_short v[56:57], v0, off offset:3072
	v_cvt_pk_bf16_f32 v0, v12, s0
	global_store_short v[58:59], v0, off offset:3072
	v_cvt_pk_bf16_f32 v0, v29, s0
	global_store_short v[56:57], v0, off offset:3200
	v_cvt_pk_bf16_f32 v0, v13, s0
	global_store_short v[58:59], v0, off offset:3200
	v_cvt_pk_bf16_f32 v0, v30, s0
	global_store_short v[56:57], v0, off offset:3328
	v_cvt_pk_bf16_f32 v0, v14, s0
	global_store_short v[58:59], v0, off offset:3328
	v_cvt_pk_bf16_f32 v0, v31, s0
	global_store_short v[56:57], v0, off offset:3456
	v_cvt_pk_bf16_f32 v0, v15, s0
	s_and_b64 vcc, exec, s[18:19]
	s_mov_b32 s16, s22
	global_store_short v[58:59], v0, off offset:3456
	s_barrier
	s_cbranch_vccz .LBB0_748

.LBB0_865:
	s_add_i32 s34, s8, s66
	s_cmpk_gt_i32 s34, 0x3ff
	s_cselect_b32 s67, 1, 0
	s_and_b32 s68, s34, 0x60
	s_cselect_b32 s68, 0, 1
	s_cmp_eq_u32 s28, 0x100
	s_cselect_b32 s67, s68, s67
	s_cmp_lg_u32 s67, 0
	s_cselect_b64 s[38:39], -1, 0
	v_add_u32_e32 v0, v105, v131
	s_and_b64 vcc, exec, s[38:39]
	s_ashr_i32 s40, s8, 9
	s_ashr_i32 s41, s40, 31
	s_lshl_b32 s0, s8, 7
	s_and_b32 s0, s0, 0x1f80
	s_lshl_b64 s[40:41], s[40:41], 13
	s_or_b32 s0, s40, s0
	v_mov_b32_e32 v45, s41
	v_or_b32_e32 v44, s0, v120
	s_bfe_u32 s57, s8, 0x30006
	v_lshlrev_b64 v[44:45], 10, v[44:45]
	v_lshl_add_u64 v[44:45], s[10:11], 0, v[44:45]
	s_lshl_b32 s0, s57, 7
	v_lshl_add_u64 v[44:45], v[44:45], 0, s[0:1]
	v_lshl_add_u64 v[44:45], v[44:45], 0, v[108:109]
	global_load_dwordx4 v[88:91], v[44:45], off
	global_load_dwordx4 v[92:95], v[44:45], off offset:32
	s_lshl_b32 s57, s57, 2
	v_mov_b32_e32 v46, s57
	global_load_dword v128, v46, s[50:51]
	global_load_dword v129, v46, s[52:53]
	global_load_dwordx4 v[96:99], v[44:45], off offset:64
	global_load_dwordx4 v[100:103], v[44:45], off offset:96
	s_waitcnt vmcnt(15)
	ds_write_b128 v134, v[48:51]
	s_waitcnt vmcnt(9)
	ds_write_b128 v134, v[72:75] offset:53248
	s_waitcnt vmcnt(8)
	ds_write_b128 v135, v[76:79]
	ds_write_b128 v134, v[52:55] offset:9216
	s_waitcnt vmcnt(7)
	ds_write_b128 v134, v[80:83] offset:62464
	s_waitcnt vmcnt(6)
	ds_write_b128 v135, v[84:87] offset:9216
	ds_write_b16 v0, v56 offset:18432
	ds_write_b16_d16_hi v0, v56 offset:18704
	ds_write_b16 v0, v57 offset:18976
	ds_write_b16_d16_hi v0, v57 offset:19248
	ds_write_b16 v0, v58 offset:19520
	ds_write_b16_d16_hi v0, v58 offset:19792
	ds_write_b16 v0, v59 offset:20064
	ds_write_b16_d16_hi v0, v59 offset:20336
	ds_write_b16 v136, v60 offset:18432
	ds_write_b16_d16_hi v136, v60 offset:18704
	ds_write_b16 v136, v61 offset:18976
	ds_write_b16_d16_hi v136, v61 offset:19248
	ds_write_b16 v136, v62 offset:19520
	ds_write_b16_d16_hi v136, v62 offset:19792
	ds_write_b16 v136, v63 offset:20064
	ds_write_b16_d16_hi v136, v63 offset:20336
	ds_write_b16 v136, v64 offset:27136
	ds_write_b16_d16_hi v136, v64 offset:27408
	ds_write_b16 v136, v65 offset:27680
	ds_write_b16_d16_hi v136, v65 offset:27952
	ds_write_b16 v136, v66 offset:28224
	ds_write_b16_d16_hi v136, v66 offset:28496
	ds_write_b16 v136, v67 offset:28768
	ds_write_b16_d16_hi v136, v67 offset:29040
	ds_write_b16 v136, v68 offset:35840
	ds_write_b16_d16_hi v136, v68 offset:36112
	ds_write_b16 v136, v69 offset:36384
	ds_write_b16_d16_hi v136, v69 offset:36656
	ds_write_b16 v136, v70 offset:36928
	ds_write_b16_d16_hi v136, v70 offset:37200
	ds_write_b16 v136, v71 offset:37472
	ds_write_b16_d16_hi v136, v71 offset:37744
	s_waitcnt lgkmcnt(0)
	s_barrier
	s_waitcnt vmcnt(0)
	s_cbranch_vccnz .LBB0_867
	s_ashr_i32 s40, s34, 9
	s_and_b32 s0, s34, 63
	s_ashr_i32 s41, s40, 31
	s_lshl_b64 s[40:41], s[40:41], 13
	s_lshl_b32 s0, s0, 7
	s_bfe_u32 s9, s34, 0x30006
	s_or_b32 s40, s40, s0
	v_lshl_add_u64 v[0:1], s[40:41], 0, v[106:107]
	s_lshl_b32 s0, s9, 7
	v_lshl_add_u64 v[2:3], v[116:117], 0, s[0:1]
	v_lshlrev_b64 v[0:1], 10, v[0:1]
	v_lshl_add_u64 v[0:1], v[2:3], 0, v[0:1]
	v_add_co_u32_e32 v2, vcc, s23, v0
	s_lshl_b32 s0, s9, 8
	s_nop 0
	v_addc_co_u32_e32 v3, vcc, 0, v1, vcc
	global_load_dwordx4 v[48:51], v[0:1], off
	global_load_dwordx4 v[52:55], v[2:3], off
	v_mov_b32_e32 v1, s41
	v_or_b32_e32 v0, s40, v104
	v_lshlrev_b64 v[0:1], 11, v[0:1]
	v_lshl_add_u64 v[0:1], s[12:13], 0, v[0:1]
	v_lshl_add_u64 v[0:1], v[0:1], 0, s[0:1]
	s_ashr_i32 s35, s34, 31
	s_add_i32 s46, s34, 0x400
	v_lshl_add_u64 v[0:1], v[110:111], 1, v[0:1]
	s_lshl_b64 s[40:41], s[34:35], 14
	s_ashr_i32 s47, s46, 31
	global_load_dwordx4 v[56:59], v[0:1], off
	global_load_dwordx4 v[60:63], v[0:1], off offset:64
	global_load_dwordx4 v[64:67], v[0:1], off offset:128
	global_load_dwordx4 v[68:71], v[0:1], off offset:192
	s_lshl_b64 s[46:47], s[46:47], 14
	v_lshl_add_u64 v[0:1], v[118:119], 0, s[40:41]
	v_lshl_add_u64 v[2:3], v[118:119], 0, s[46:47]
	v_lshl_add_u64 v[4:5], v[0:1], 0, v[112:113]
	v_lshl_add_u64 v[0:1], v[0:1], 0, v[114:115]
	v_lshl_add_u64 v[6:7], v[2:3], 0, v[112:113]
	global_load_dwordx4 v[72:75], v[4:5], off
	global_load_dwordx4 v[76:79], v[6:7], off
	v_lshl_add_u64 v[2:3], v[2:3], 0, v[114:115]
	global_load_dwordx4 v[80:83], v[0:1], off
	global_load_dwordx4 v[84:87], v[2:3], off
.LBB0_867:
	s_ashr_i32 s40, s8, 9
	s_ashr_i32 s41, s40, 31
	s_lshl_b32 s0, s8, 7
	s_and_b32 s0, s0, 0x1f80
	s_lshl_b64 s[40:41], s[40:41], 13
	s_or_b32 s0, s40, s0
	v_mov_b32_e32 v1, s41
	v_or_b32_e32 v0, s0, v120
	s_bfe_u32 s8, s8, 0x30006
	v_lshlrev_b64 v[126:127], 10, v[0:1]
	v_lshl_add_u64 v[0:1], s[10:11], 0, v[126:127]
	s_lshl_b32 s0, s8, 7
	v_lshl_add_u64 v[0:1], v[0:1], 0, s[0:1]
	v_lshl_add_u64 v[40:41], v[0:1], 0, v[108:109]
	s_lshl_b32 s8, s8, 2
	v_mov_b32_e32 v0, s8
	ds_read_b128 v[0:3], v137 offset:53248
	ds_read_b128 v[32:35], v137 offset:53280
	ds_read_b128 v[16:19], v137 offset:57856
	ds_read_b128 v[36:39], v137 offset:57888
	ds_read_b128 v[40:43], v137 offset:53312
	ds_read_b128 v[44:47], v137 offset:53344
	s_mov_b32 s35, 0
	s_waitcnt lgkmcnt(5)
	v_mfma_f32_32x32x16_bf16 v[0:15], v[0:3], v[88:91], 0
	v_mul_f32_e32 v146, 0x3fb8aa3b, v128
	v_mul_f32_e32 v147, 0x3fb8aa3b, v129
	v_fma_f32 v148, v128, s3, -v146
	v_rndne_f32_e32 v149, v146
	v_fma_f32 v150, v129, s3, -v147
	s_waitcnt lgkmcnt(3)
	v_mfma_f32_32x32x16_bf16 v[16:31], v[16:19], v[88:91], 0
	v_fmac_f32_e32 v148, 0x32a5705f, v128
	v_fmac_f32_e32 v150, 0x32a5705f, v129
	v_cmp_ngt_f32_e32 vcc, s42, v128
	v_mfma_f32_32x32x16_bf16 v[0:15], v[32:35], v[92:95], v[0:15]
	ds_read_b128 v[32:35], v137 offset:57920
	ds_read_b128 v[142:145], v137 offset:57952
	s_waitcnt lgkmcnt(4)
	v_mfma_f32_32x32x16_bf16 v[16:31], v[36:39], v[92:95], v[16:31]
	v_rndne_f32_e32 v36, v147
	v_sub_f32_e32 v37, v146, v149
	v_sub_f32_e32 v39, v147, v36
	v_add_f32_e32 v37, v37, v148
	v_cvt_i32_f32_e32 v38, v149
	v_add_f32_e32 v39, v39, v150
	v_exp_f32_e32 v37, v37
	s_waitcnt lgkmcnt(3)
	v_mfma_f32_32x32x16_bf16 v[0:15], v[40:43], v[96:99], v[0:15]
	v_cvt_i32_f32_e32 v36, v36
	v_exp_f32_e32 v39, v39
	v_ldexp_f32 v37, v37, v38
	ds_read_b128 v[146:149], v138
	ds_read_b128 v[150:153], v138 offset:32
	ds_read_b128 v[154:157], v138 offset:4608
	ds_read_b128 v[158:161], v138 offset:4640
	s_waitcnt lgkmcnt(5)
	v_mfma_f32_32x32x16_bf16 v[16:31], v[32:35], v[96:99], v[16:31]
	v_ldexp_f32 v32, v39, v36
	v_cndmask_b32_e32 v33, 0, v37, vcc
	v_cmp_ngt_f32_e32 vcc, s42, v129
	s_nop 1
	v_cndmask_b32_e32 v34, 0, v32, vcc
	v_cmp_nlt_f32_e32 vcc, s43, v128
	v_mfma_f32_32x32x16_bf16 v[0:15], v[44:47], v[100:103], v[0:15]
	v_cndmask_b32_e32 v32, v141, v33, vcc
	v_cmp_nlt_f32_e32 vcc, s43, v129
	s_nop 1
	v_cndmask_b32_e32 v33, v141, v34, vcc
	v_mul_f32_e64 v128, v32, s22
	v_mul_f32_e64 v129, v33, s22
	s_waitcnt lgkmcnt(4)
	v_mfma_f32_32x32x16_bf16 v[16:31], v[142:145], v[100:103], v[16:31]
	v_mul_f32_e64 v162, v128, v122
	v_mul_f32_e64 v163, v129, v123
	v_mov_b32_e32 v142, v121
	v_sub_f32_e32 v32, v162, v163
	v_exp_f32_e32 v162, v32
	v_mov_b32_e32 v143, v133
	v_pk_mul_f32 v[32:33], v[162:163], v[0:1] op_sel_hi:[0,1]
	v_pk_mul_f32 v[46:47], v[162:163], v[14:15] op_sel_hi:[0,1]
	v_pk_mul_f32 v[44:45], v[162:163], v[12:13] op_sel_hi:[0,1]
	v_pk_mul_f32 v[42:43], v[162:163], v[10:11] op_sel_hi:[0,1]
	v_pk_mul_f32 v[40:41], v[162:163], v[8:9] op_sel_hi:[0,1]
	v_pk_mul_f32 v[38:39], v[162:163], v[6:7] op_sel_hi:[0,1]
	v_pk_mul_f32 v[36:37], v[162:163], v[4:5] op_sel_hi:[0,1]
	v_pk_mul_f32 v[34:35], v[162:163], v[2:3] op_sel_hi:[0,1]
	v_pk_mul_f32 v[0:1], v[162:163], v[16:17] op_sel_hi:[0,1]
	v_pk_mul_f32 v[14:15], v[162:163], v[30:31] op_sel_hi:[0,1]
	s_waitcnt lgkmcnt(3)
	v_mfma_f32_32x32x16_bf16 v[32:47], v[146:149], v[88:91], v[32:47]
	v_mul_f32_e64 v12, v162, v28
	v_mul_f32_e64 v13, v162, v29
	v_mul_f32_e64 v10, v162, v26
	v_mul_f32_e64 v11, v162, v27
	v_mul_f32_e64 v8, v162, v24
	v_mul_f32_e64 v9, v162, v25
	v_pk_mul_f32 v[6:7], v[162:163], v[22:23] op_sel_hi:[0,1]
	v_pk_mul_f32 v[4:5], v[162:163], v[20:21] op_sel_hi:[0,1]
	v_pk_mul_f32 v[2:3], v[162:163], v[18:19] op_sel_hi:[0,1]
	ds_read_b128 v[16:19], v138 offset:64
	ds_read_b128 v[20:23], v138 offset:96
	s_waitcnt lgkmcnt(3)
	v_mfma_f32_32x32x16_bf16 v[0:15], v[154:157], v[88:91], v[0:15]
	v_mfma_f32_32x32x16_bf16 v[32:47], v[150:153], v[92:95], v[32:47]
	s_waitcnt lgkmcnt(2)
	v_mfma_f32_32x32x16_bf16 v[0:15], v[158:161], v[92:95], v[0:15]
	s_waitcnt lgkmcnt(1)
	v_mfma_f32_32x32x16_bf16 v[32:47], v[16:19], v[96:99], v[32:47]
	ds_read_b128 v[16:19], v138 offset:4672
	ds_read_b128 v[24:27], v138 offset:4704
	s_waitcnt lgkmcnt(1)
	v_mfma_f32_32x32x16_bf16 v[0:15], v[16:19], v[96:99], v[0:15]
	v_exp_f32_e32 v16, v163
	v_mfma_f32_32x32x16_bf16 v[32:47], v[20:23], v[100:103], v[32:47]
	s_waitcnt lgkmcnt(0)
	v_mfma_f32_32x32x16_bf16 v[0:15], v[24:27], v[100:103], v[0:15]
	s_nop 9
	v_mul_f32_e64 v30, v16, v46
	v_mul_f32_e64 v31, v16, v47
	v_mul_f32_e64 v28, v16, v44
	v_mul_f32_e64 v29, v16, v45
	v_mul_f32_e64 v26, v16, v42
	v_mul_f32_e64 v27, v16, v43
	v_pk_mul_f32 v[24:25], v[16:17], v[40:41] op_sel_hi:[0,1]
	v_pk_mul_f32 v[22:23], v[16:17], v[38:39] op_sel_hi:[0,1]
	v_pk_mul_f32 v[20:21], v[16:17], v[36:37] op_sel_hi:[0,1]
	v_pk_mul_f32 v[18:19], v[16:17], v[34:35] op_sel_hi:[0,1]
	v_pk_mul_f32 v[14:15], v[16:17], v[14:15] op_sel_hi:[0,1]
	v_pk_mul_f32 v[12:13], v[16:17], v[12:13] op_sel_hi:[0,1]
	v_pk_mul_f32 v[10:11], v[16:17], v[10:11] op_sel_hi:[0,1]
	v_pk_mul_f32 v[8:9], v[16:17], v[8:9] op_sel_hi:[0,1]
	v_pk_mul_f32 v[6:7], v[16:17], v[6:7] op_sel_hi:[0,1]
	v_pk_mul_f32 v[4:5], v[16:17], v[4:5] op_sel_hi:[0,1]
	v_pk_mul_f32 v[2:3], v[16:17], v[2:3] op_sel_hi:[0,1]
	v_pk_mul_f32 v[0:1], v[16:17], v[0:1] op_sel_hi:[0,1]
	v_pk_mul_f32 v[16:17], v[16:17], v[32:33] op_sel_hi:[0,1]
	s_lshl_b32 s56, s33, 4
	s_add_i32 s56, s56, 0x18000
	v_and_b32_e32 v34, 63, v104
	v_sub_u32_e32 v35, 0x7f, v34
	v_subrev_u32_e32 v36, 63, v34
	v_sub_u32_e32 v37, 63, v34
	v_add_u32_e32 v38, 1, v34
	v_add_u32_e32 v39, 0x41, v34
	v_max_i32_e32 v37, v36, v37
	v_cmp_gt_i32_e32 vcc, 0, v36
	v_cvt_f32_u32_e32 v35, v35
	v_cvt_f32_u32_e32 v37, v37
	v_cvt_f32_u32_e32 v38, v38
	v_cvt_f32_u32_e32 v39, v39
	v_cndmask_b32_e32 v36, v128, v129, vcc
	v_mul_f32_e32 v35, v129, v35
	v_mul_f32_e32 v36, v36, v37
	v_mul_f32_e32 v38, v128, v38
	v_mul_f32_e32 v39, v128, v39
	v_exp_f32_e32 v35, v35
	v_exp_f32_e32 v36, v36
	v_exp_f32_e32 v38, v38
	v_exp_f32_e32 v39, v39
	v_lshl_add_u32 v40, v34, 2, s56
	v_add_u32_e32 v224, 4, v132
	v_lshl_add_u32 v224, v224, 2, s56
	ds_write_b32 v40, v35
	ds_write_b32 v40, v36 offset:256
	ds_write_b32 v40, v38 offset:512
	ds_write_b32 v40, v39 offset:768
	ds_read_b128 v[144:147], v142
	ds_read_b128 v[148:151], v142 offset:32
	ds_read_b128 v[152:155], v142 offset:64
	ds_read_b128 v[156:159], v142 offset:96
	ds_read_b32 v160, v224 offset:492
	ds_read_b32 v161, v224 offset:488
	ds_read_b32 v162, v224 offset:484
	ds_read_b32 v163, v224 offset:480
	ds_read_b32 v164, v224 offset:460
	ds_read_b32 v165, v224 offset:456
	ds_read_b32 v166, v224 offset:452
	ds_read_b32 v167, v224 offset:448
	ds_read_b32 v168, v224 offset:428
	ds_read_b32 v169, v224 offset:424
	ds_read_b32 v170, v224 offset:420
	ds_read_b32 v171, v224 offset:416
	ds_read_b32 v172, v224 offset:396
	ds_read_b32 v173, v224 offset:392
	ds_read_b32 v174, v224 offset:388
	ds_read_b32 v175, v224 offset:384
	s_waitcnt lgkmcnt(0)
	v_mfma_f32_32x32x16_bf16 v[32:47], v[144:147], v[88:91], 0
	v_mfma_f32_32x32x16_bf16 v[32:47], v[148:151], v[92:95], v[32:47]
	v_mfma_f32_32x32x16_bf16 v[32:47], v[152:155], v[96:99], v[32:47]
	v_mfma_f32_32x32x16_bf16 v[32:47], v[156:159], v[100:103], v[32:47]
	ds_read_b128 v[144:147], v142 offset:4608
	ds_read_b128 v[148:151], v142 offset:4640
	ds_read_b128 v[152:155], v142 offset:4672
	ds_read_b128 v[156:159], v142 offset:4704
	ds_read_b32 v176, v224 offset:364
	ds_read_b32 v177, v224 offset:360
	ds_read_b32 v178, v224 offset:356
	ds_read_b32 v179, v224 offset:352
	ds_read_b32 v180, v224 offset:332
	ds_read_b32 v181, v224 offset:328
	ds_read_b32 v182, v224 offset:324
	ds_read_b32 v183, v224 offset:320
	ds_read_b32 v184, v224 offset:300
	ds_read_b32 v185, v224 offset:296
	ds_read_b32 v186, v224 offset:292
	ds_read_b32 v187, v224 offset:288
	ds_read_b32 v188, v224 offset:268
	ds_read_b32 v189, v224 offset:264
	ds_read_b32 v190, v224 offset:260
	ds_read_b32 v191, v224 offset:256
	ds_read_b128 v[208:211], v143
	ds_read_b128 v[212:215], v143 offset:8704
	ds_read_b128 v[216:219], v143 offset:32
	ds_read_b128 v[220:223], v143 offset:8736
	s_waitcnt lgkmcnt(15)
	v_mfma_f32_32x32x16_bf16 v[192:207], v[144:147], v[88:91], 0
	v_mfma_f32_32x32x16_bf16 v[192:207], v[148:151], v[92:95], v[192:207]
	v_mfma_f32_32x32x16_bf16 v[192:207], v[152:155], v[96:99], v[192:207]
	v_mfma_f32_32x32x16_bf16 v[192:207], v[156:159], v[100:103], v[192:207]
	s_waitcnt lgkmcnt(0)
	v_pk_mul_f32 v[32:33], v[160:161], v[32:33]
	v_pk_mul_f32 v[34:35], v[162:163], v[34:35]
	v_pk_mul_f32 v[36:37], v[164:165], v[36:37]
	v_pk_mul_f32 v[38:39], v[166:167], v[38:39]
	v_pk_mul_f32 v[40:41], v[168:169], v[40:41]
	v_pk_mul_f32 v[42:43], v[170:171], v[42:43]
	v_pk_mul_f32 v[44:45], v[172:173], v[44:45]
	v_pk_mul_f32 v[46:47], v[174:175], v[46:47]
	v_cvt_pk_bf16_f32 v240, v32, v33
	v_cvt_pk_bf16_f32 v241, v34, v35
	v_cvt_pk_bf16_f32 v242, v36, v37
	v_cvt_pk_bf16_f32 v243, v38, v39
	v_cvt_pk_bf16_f32 v244, v40, v41
	v_cvt_pk_bf16_f32 v245, v42, v43
	v_cvt_pk_bf16_f32 v246, v44, v45
	v_cvt_pk_bf16_f32 v247, v46, v47
	s_nop 1
	v_mfma_f32_32x32x16_bf16 v[16:31], v[208:211], v[240:243], v[16:31]
	v_mfma_f32_32x32x16_bf16 v[0:15], v[212:215], v[240:243], v[0:15]
	v_mfma_f32_32x32x16_bf16 v[16:31], v[216:219], v[244:247], v[16:31]
	v_mfma_f32_32x32x16_bf16 v[0:15], v[220:223], v[244:247], v[0:15]
	ds_read_b128 v[144:147], v142 offset:9216
	ds_read_b128 v[148:151], v142 offset:9248
	ds_read_b128 v[152:155], v142 offset:9280
	ds_read_b128 v[156:159], v142 offset:9312
	ds_read_b32 v160, v224 offset:236
	ds_read_b32 v161, v224 offset:232
	ds_read_b32 v162, v224 offset:228
	ds_read_b32 v163, v224 offset:224
	ds_read_b32 v164, v224 offset:204
	ds_read_b32 v165, v224 offset:200
	ds_read_b32 v166, v224 offset:196
	ds_read_b32 v167, v224 offset:192
	ds_read_b32 v168, v224 offset:172
	ds_read_b32 v169, v224 offset:168
	ds_read_b32 v170, v224 offset:164
	ds_read_b32 v171, v224 offset:160
	ds_read_b32 v172, v224 offset:140
	ds_read_b32 v173, v224 offset:136
	ds_read_b32 v174, v224 offset:132
	ds_read_b32 v175, v224 offset:128
	ds_read_b128 v[208:211], v143 offset:64
	ds_read_b128 v[212:215], v143 offset:8768
	ds_read_b128 v[216:219], v143 offset:96
	ds_read_b128 v[220:223], v143 offset:8800
	s_waitcnt lgkmcnt(15)
	v_mfma_f32_32x32x16_bf16 v[32:47], v[144:147], v[88:91], 0
	v_mfma_f32_32x32x16_bf16 v[32:47], v[148:151], v[92:95], v[32:47]
	v_mfma_f32_32x32x16_bf16 v[32:47], v[152:155], v[96:99], v[32:47]
	v_mfma_f32_32x32x16_bf16 v[32:47], v[156:159], v[100:103], v[32:47]
	s_waitcnt lgkmcnt(0)
	v_pk_mul_f32 v[192:193], v[176:177], v[192:193]
	v_pk_mul_f32 v[194:195], v[178:179], v[194:195]
	v_pk_mul_f32 v[196:197], v[180:181], v[196:197]
	v_pk_mul_f32 v[198:199], v[182:183], v[198:199]
	v_pk_mul_f32 v[200:201], v[184:185], v[200:201]
	v_pk_mul_f32 v[202:203], v[186:187], v[202:203]
	v_pk_mul_f32 v[204:205], v[188:189], v[204:205]
	v_pk_mul_f32 v[206:207], v[190:191], v[206:207]
	v_cvt_pk_bf16_f32 v240, v192, v193
	v_cvt_pk_bf16_f32 v241, v194, v195
	v_cvt_pk_bf16_f32 v242, v196, v197
	v_cvt_pk_bf16_f32 v243, v198, v199
	v_cvt_pk_bf16_f32 v244, v200, v201
	v_cvt_pk_bf16_f32 v245, v202, v203
	v_cvt_pk_bf16_f32 v246, v204, v205
	v_cvt_pk_bf16_f32 v247, v206, v207
	s_nop 1
	v_mfma_f32_32x32x16_bf16 v[16:31], v[208:211], v[240:243], v[16:31]
	v_mfma_f32_32x32x16_bf16 v[0:15], v[212:215], v[240:243], v[0:15]
	v_mfma_f32_32x32x16_bf16 v[16:31], v[216:219], v[244:247], v[16:31]
	v_mfma_f32_32x32x16_bf16 v[0:15], v[220:223], v[244:247], v[0:15]
	ds_read_b128 v[144:147], v142 offset:13824
	ds_read_b128 v[148:151], v142 offset:13856
	ds_read_b128 v[152:155], v142 offset:13888
	ds_read_b128 v[156:159], v142 offset:13920
	ds_read_b32 v176, v224 offset:108
	ds_read_b32 v177, v224 offset:104
	ds_read_b32 v178, v224 offset:100
	ds_read_b32 v179, v224 offset:96
	ds_read_b32 v180, v224 offset:76
	ds_read_b32 v181, v224 offset:72
	ds_read_b32 v182, v224 offset:68
	ds_read_b32 v183, v224 offset:64
	ds_read_b32 v184, v224 offset:44
	ds_read_b32 v185, v224 offset:40
	ds_read_b32 v186, v224 offset:36
	ds_read_b32 v187, v224 offset:32
	ds_read_b32 v188, v224 offset:12
	ds_read_b32 v189, v224 offset:8
	ds_read_b32 v190, v224 offset:4
	ds_read_b32 v191, v224
	ds_read_b128 v[208:211], v143 offset:128
	ds_read_b128 v[212:215], v143 offset:8832
	ds_read_b128 v[216:219], v143 offset:160
	ds_read_b128 v[220:223], v143 offset:8864
	s_waitcnt lgkmcnt(15)
	v_mfma_f32_32x32x16_bf16 v[192:207], v[144:147], v[88:91], 0
	v_mfma_f32_32x32x16_bf16 v[192:207], v[148:151], v[92:95], v[192:207]
	v_mfma_f32_32x32x16_bf16 v[192:207], v[152:155], v[96:99], v[192:207]
	v_mfma_f32_32x32x16_bf16 v[192:207], v[156:159], v[100:103], v[192:207]
	s_waitcnt lgkmcnt(0)
	v_pk_mul_f32 v[32:33], v[160:161], v[32:33]
	v_pk_mul_f32 v[34:35], v[162:163], v[34:35]
	v_pk_mul_f32 v[36:37], v[164:165], v[36:37]
	v_pk_mul_f32 v[38:39], v[166:167], v[38:39]
	v_pk_mul_f32 v[40:41], v[168:169], v[40:41]
	v_pk_mul_f32 v[42:43], v[170:171], v[42:43]
	v_pk_mul_f32 v[44:45], v[172:173], v[44:45]
	v_pk_mul_f32 v[46:47], v[174:175], v[46:47]
	v_cvt_pk_bf16_f32 v240, v32, v33
	v_cvt_pk_bf16_f32 v241, v34, v35
	v_cvt_pk_bf16_f32 v242, v36, v37
	v_cvt_pk_bf16_f32 v243, v38, v39
	v_cvt_pk_bf16_f32 v244, v40, v41
	v_cvt_pk_bf16_f32 v245, v42, v43
	v_cvt_pk_bf16_f32 v246, v44, v45
	v_cvt_pk_bf16_f32 v247, v46, v47
	s_nop 1
	v_mfma_f32_32x32x16_bf16 v[16:31], v[208:211], v[240:243], v[16:31]
	v_mfma_f32_32x32x16_bf16 v[0:15], v[212:215], v[240:243], v[0:15]
	v_mfma_f32_32x32x16_bf16 v[16:31], v[216:219], v[244:247], v[16:31]
	v_mfma_f32_32x32x16_bf16 v[0:15], v[220:223], v[244:247], v[0:15]
	ds_read_b128 v[208:211], v143 offset:192
	ds_read_b128 v[212:215], v143 offset:8896
	ds_read_b128 v[216:219], v143 offset:224
	ds_read_b128 v[220:223], v143 offset:8928
	s_waitcnt lgkmcnt(0)
	v_pk_mul_f32 v[192:193], v[176:177], v[192:193]
	v_pk_mul_f32 v[194:195], v[178:179], v[194:195]
	v_pk_mul_f32 v[196:197], v[180:181], v[196:197]
	v_pk_mul_f32 v[198:199], v[182:183], v[198:199]
	v_pk_mul_f32 v[200:201], v[184:185], v[200:201]
	v_pk_mul_f32 v[202:203], v[186:187], v[202:203]
	v_pk_mul_f32 v[204:205], v[188:189], v[204:205]
	v_pk_mul_f32 v[206:207], v[190:191], v[206:207]
	v_cvt_pk_bf16_f32 v240, v192, v193
	v_cvt_pk_bf16_f32 v241, v194, v195
	v_cvt_pk_bf16_f32 v242, v196, v197
	v_cvt_pk_bf16_f32 v243, v198, v199
	v_cvt_pk_bf16_f32 v244, v200, v201
	v_cvt_pk_bf16_f32 v245, v202, v203
	v_cvt_pk_bf16_f32 v246, v204, v205
	v_cvt_pk_bf16_f32 v247, v206, v207
	s_nop 1
	v_mfma_f32_32x32x16_bf16 v[16:31], v[208:211], v[240:243], v[16:31]
	v_mfma_f32_32x32x16_bf16 v[0:15], v[212:215], v[240:243], v[0:15]
	v_mfma_f32_32x32x16_bf16 v[16:31], v[216:219], v[244:247], v[16:31]
	v_mfma_f32_32x32x16_bf16 v[0:15], v[220:223], v[244:247], v[0:15]
	s_movk_i32 s35, 0xff80
	s_nop 3
	s_nop 6
	v_mul_f32_e32 v32, v17, v17
	v_fmac_f32_e32 v32, v16, v16
	v_fmac_f32_e32 v32, v18, v18
	v_fmac_f32_e32 v32, v19, v19
	v_fmac_f32_e32 v32, v20, v20
	v_fmac_f32_e32 v32, v21, v21
	v_fmac_f32_e32 v32, v22, v22
	v_fmac_f32_e32 v32, v23, v23
	v_fmac_f32_e32 v32, v24, v24
	v_fmac_f32_e32 v32, v25, v25
	v_fmac_f32_e32 v32, v26, v26
	v_fmac_f32_e32 v32, v27, v27
	v_fmac_f32_e32 v32, v28, v28
	v_fmac_f32_e32 v32, v29, v29
	v_fmac_f32_e32 v32, v30, v30
	v_fmac_f32_e32 v32, v31, v31
	v_fmac_f32_e32 v32, v0, v0
	v_fmac_f32_e32 v32, v1, v1
	v_fmac_f32_e32 v32, v2, v2
	v_fmac_f32_e32 v32, v3, v3
	v_fmac_f32_e32 v32, v4, v4
	v_fmac_f32_e32 v32, v5, v5
	v_fmac_f32_e32 v32, v6, v6
	v_fmac_f32_e32 v32, v7, v7
	v_fmac_f32_e32 v32, v8, v8
	v_fmac_f32_e32 v32, v9, v9
	v_fmac_f32_e32 v32, v10, v10
	v_fmac_f32_e32 v32, v11, v11
	v_fmac_f32_e32 v32, v12, v12
	v_fmac_f32_e32 v32, v13, v13
	v_fmac_f32_e32 v32, v14, v14
	v_fmac_f32_e32 v32, v15, v15
	v_mov_b32_e32 v33, v32
	s_nop 1
	v_permlane32_swap_b32_e32 v32, v33
	v_add_f32_e32 v36, v32, v33
	s_and_saveexec_b64 s[40:41], s[6:7]
	s_cbranch_execz .LBB0_864
	ds_write_b32 v139, v36
	s_branch .LBB0_864
